# P2/P7 residual epilogue: second-half residual loads issued a quarter into the first half (into dead accumulator registers) and copied, instead of after the first half
# speedup vs baseline: 1.0028x; 1.0028x over previous
; __device__ __forceinline__ unsigned cvt_pk_bf16(float lo, float hi) { unsigned r; asm volatile("v_cvt_pk_bf16_f32 %0, %1, %2" : "=v"(r) : "v"(lo), "v"(hi)); return r; }
;     __device__ __forceinline__ void operator()(const f32x4 (&acc)[2][2][4][2], const Unit& u, int wr, int wc, int fr, int fq) const {
;         const int row0 = u.pm * BM + wr * 64 + fr, col0 = u.pn * BM + wc * 32 + 8 * fq;
; #pragma unroll
;         for (int ai = 0; ai < 2; ++ai) {
;         u32x4 xin[1][4][2];
;         if (XI_BF16) {
; #pragma unroll
;                 for (int m = 0; m < 4; ++m)
; #pragma unroll
;                     for (int bj = 0; bj < 2; ++bj) xin[0][m][bj] = *(const u32x4*)(xb + (size_t)(row0 + ai * HALF + m * 16) * DM + col0 + bj * HALF);
;         }
; #pragma unroll
;             for (int m = 0; m < 4; ++m) {
;                 const int row = row0 + ai * HALF + m * 16; const size_t off = (size_t)row * DM + col0; float q = 0.f;
; #pragma unroll
;                 for (int bj = 0; bj < 2; ++bj) {
;                     const size_t o2 = off + bj * HALF; f32x4 b0, b1;
;                     if (XI_BF16) bf8_to_f32(xin[0][m][bj], b0, b1); else { b0 = *(const f32x4*)(xi + o2); b1 = *(const f32x4*)(xi + o2 + 4); }
;                     const f32x4 o0 = b0 + acc[ai][bj][m][0] * scale, o1 = b1 + acc[ai][bj][m][1] * scale;
;                     u32x4 w; w.x = cvt_pk_bf16(o0[0], o0[1]); w.y = cvt_pk_bf16(o0[2], o0[3]); w.z = cvt_pk_bf16(o1[0], o1[1]); w.w = cvt_pk_bf16(o1[2], o1[3]);
;                     *(u32x4*)(xb + o2) = w;
;                     q += ((o0[0] * o0[0] + o0[1] * o0[1]) + (o0[2] * o0[2] + o0[3] * o0[3])) + ((o1[0] * o1[0] + o1[1] * o1[1]) + (o1[2] * o1[2] + o1[3] * o1[3]));
;                 }
;                 q += __shfl_xor(q, 16); q += __shfl_xor(q, 32);
;                 if (fq == 0) ssout[(size_t)row * 16 + u.pn * 4 + wc] = q;
.LBB0_377:
	s_or_b64 exec, exec, s[24:25]
	v_add_u32_e32 v126, 0x80, v188
	v_ashrrev_i32_e32 v127, 31, v126
	v_lshlrev_b64 v[126:127], 11, v[126:127]
	v_lshl_add_u64 v[126:127], v[186:187], 0, v[126:127]
	global_load_dwordx4 v[122:125], v[126:127], off
	global_load_dwordx4 v[206:209], v[126:127], off offset:256
	v_add_u32_e32 v238, 0x90, v188
	v_ashrrev_i32_e32 v239, 31, v238
	v_lshlrev_b64 v[238:239], 11, v[238:239]
	v_lshl_add_u64 v[238:239], v[186:187], 0, v[238:239]
	global_load_dwordx4 v[210:213], v[238:239], off
	global_load_dwordx4 v[214:217], v[238:239], off offset:256
	v_add_u32_e32 v126, 0xa0, v188
	v_ashrrev_i32_e32 v127, 31, v126
	v_lshlrev_b64 v[126:127], 11, v[126:127]
	v_lshl_add_u64 v[126:127], v[186:187], 0, v[126:127]
	global_load_dwordx4 v[218:221], v[126:127], off
	global_load_dwordx4 v[222:225], v[126:127], off offset:256
	v_add_u32_e32 v238, 0xb0, v188
	v_ashrrev_i32_e32 v239, 31, v238
	v_lshlrev_b64 v[238:239], 11, v[238:239]
	v_lshl_add_u64 v[238:239], v[186:187], 0, v[238:239]
	global_load_dwordx4 v[226:229], v[238:239], off
	global_load_dwordx4 v[248:251], v[238:239], off offset:256
	s_waitcnt lgkmcnt(0)
	v_lshlrev_b32_e32 v114, 16, v148
	v_and_b32_e32 v115, 0xffff0000, v148
	v_lshlrev_b32_e32 v116, 16, v149
	v_and_b32_e32 v117, 0xffff0000, v149
	v_lshlrev_b32_e32 v118, 16, v150
	v_and_b32_e32 v119, 0xffff0000, v150
	v_pk_fma_f32 v[108:109], v[108:109], 0.5, v[114:115] op_sel_hi:[1,0,1]
	v_pk_fma_f32 v[110:111], v[110:111], 0.5, v[116:117] op_sel_hi:[1,0,1]
	v_pk_fma_f32 v[116:117], v[104:105], 0.5, v[118:119] op_sel_hi:[1,0,1]
	v_cvt_pk_bf16_f32 v104, v108, v109
	v_mul_f32_e32 v109, v109, v109
	v_lshlrev_b32_e32 v120, 16, v151
	v_and_b32_e32 v121, 0xffff0000, v151
	v_fmac_f32_e32 v109, v108, v108
	v_mul_f32_e32 v108, v111, v111
	v_pk_fma_f32 v[114:115], v[106:107], 0.5, v[120:121] op_sel_hi:[1,0,1]
	v_fmac_f32_e32 v108, v110, v110
	v_cvt_pk_bf16_f32 v105, v110, v111
	v_add_f32_e32 v108, v109, v108
	v_mul_f32_e32 v109, v117, v117
	v_mul_f32_e32 v110, v115, v115
	v_fmac_f32_e32 v109, v116, v116
	v_fmac_f32_e32 v110, v114, v114
	v_add_f32_e32 v109, v109, v110
	v_add_f32_e32 v113, v108, v109
	v_lshlrev_b32_e32 v108, 16, v144
	v_and_b32_e32 v109, 0xffff0000, v144
	v_lshlrev_b32_e32 v110, 16, v145
	v_and_b32_e32 v111, 0xffff0000, v145
	v_cvt_pk_bf16_f32 v106, v116, v117
	v_cvt_pk_bf16_f32 v107, v114, v115
	v_lshlrev_b32_e32 v114, 16, v146
	v_and_b32_e32 v115, 0xffff0000, v146
	v_pk_fma_f32 v[102:103], v[102:103], 0.5, v[110:111] op_sel_hi:[1,0,1]
	v_pk_fma_f32 v[100:101], v[100:101], 0.5, v[108:109] op_sel_hi:[1,0,1]
	v_lshlrev_b32_e32 v116, 16, v147
	v_and_b32_e32 v117, 0xffff0000, v147
	v_pk_fma_f32 v[110:111], v[96:97], 0.5, v[114:115] op_sel_hi:[1,0,1]
	v_mul_f32_e32 v96, v101, v101
	v_mul_f32_e32 v97, v103, v103
	v_pk_fma_f32 v[108:109], v[98:99], 0.5, v[116:117] op_sel_hi:[1,0,1]
	v_fmac_f32_e32 v96, v100, v100
	v_fmac_f32_e32 v97, v102, v102
	v_add_f32_e32 v96, v96, v97
	v_mul_f32_e32 v97, v111, v111
	v_mul_f32_e32 v98, v109, v109
	v_fmac_f32_e32 v97, v110, v110
	v_fmac_f32_e32 v98, v108, v108
	v_add_f32_e32 v97, v97, v98
	v_add_f32_e32 v96, v96, v97
	v_add_f32_e32 v99, v113, v96
	ds_bpermute_b32 v113, v204, v99
	v_lshl_add_u64 v[96:97], s[76:77], 0, v[200:201]
	v_lshl_add_u64 v[114:115], v[184:185], 1, v[96:97]
	global_store_dwordx4 v[114:115], v[104:107], off
	v_cvt_pk_bf16_f32 v98, v100, v101
	s_waitcnt lgkmcnt(0)
	v_add_f32_e32 v96, v99, v113
	ds_bpermute_b32 v97, v112, v96
	v_cvt_pk_bf16_f32 v99, v102, v103
	v_cvt_pk_bf16_f32 v100, v110, v111
	v_cvt_pk_bf16_f32 v101, v108, v109
	global_store_dwordx4 v[114:115], v[98:101], off offset:256
	s_and_saveexec_b64 s[24:25], s[8:9]
	s_cbranch_execz .LBB0_379
	v_lshlrev_b64 v[98:99], 6, v[198:199]
	v_lshl_add_u64 v[98:99], s[14:15], 0, v[98:99]
	v_lshl_add_u64 v[98:99], s[20:21], 2, v[98:99]
	s_lshl_b32 s4, s34, 2
	v_lshl_add_u64 v[98:99], v[98:99], 0, s[4:5]
	s_waitcnt lgkmcnt(0)
	v_add_f32_e32 v96, v96, v97
	global_store_dword v[98:99], v96, off

; __device__ __forceinline__ unsigned cvt_pk_bf16(float lo, float hi) { unsigned r; asm volatile("v_cvt_pk_bf16_f32 %0, %1, %2" : "=v"(r) : "v"(lo), "v"(hi)); return r; }
;     __device__ __forceinline__ void operator()(const f32x4 (&acc)[2][2][4][2], const Unit& u, int wr, int wc, int fr, int fq) const {
;     ...
;         for (int ai = 0; ai < 2; ++ai) {
;         u32x4 xin[1][4][2];
;         if (XI_BF16) {
; #pragma unroll
;                 for (int m = 0; m < 4; ++m)
; #pragma unroll
;                     for (int bj = 0; bj < 2; ++bj) xin[0][m][bj] = *(const u32x4*)(xb + (size_t)(row0 + ai * HALF + m * 16) * DM + col0 + bj * HALF);
;         }
; #pragma unroll
;             for (int m = 0; m < 4; ++m) {
;                 const int row = row0 + ai * HALF + m * 16; const size_t off = (size_t)row * DM + col0; float q = 0.f;
; #pragma unroll
;                 for (int bj = 0; bj < 2; ++bj) {
;                     const size_t o2 = off + bj * HALF; f32x4 b0, b1;
;                     if (XI_BF16) bf8_to_f32(xin[0][m][bj], b0, b1); else { b0 = *(const f32x4*)(xi + o2); b1 = *(const f32x4*)(xi + o2 + 4); }
;                     const f32x4 o0 = b0 + acc[ai][bj][m][0] * scale, o1 = b1 + acc[ai][bj][m][1] * scale;
;                     u32x4 w; w.x = cvt_pk_bf16(o0[0], o0[1]); w.y = cvt_pk_bf16(o0[2], o0[3]); w.z = cvt_pk_bf16(o1[0], o1[1]); w.w = cvt_pk_bf16(o1[2], o1[3]);
;                     *(u32x4*)(xb + o2) = w;
;                     q += ((o0[0] * o0[0] + o0[1] * o0[1]) + (o0[2] * o0[2] + o0[3] * o0[3])) + ((o1[0] * o1[0] + o1[1] * o1[1]) + (o1[2] * o1[2] + o1[3] * o1[3]));
;                 }
;                 q += __shfl_xor(q, 16); q += __shfl_xor(q, 32);
;                 if (fq == 0) ssout[(size_t)row * 16 + u.pn * 4 + wc] = q;
.LBB0_383:
	s_or_b64 exec, exec, s[24:25]
	v_add_u32_e32 v100, 0x80, v188
	v_ashrrev_i32_e32 v101, 31, v100
	v_lshlrev_b64 v[110:111], 11, v[100:101]
	s_waitcnt lgkmcnt(0)
	v_lshl_add_u64 v[64:65], v[186:187], 0, v[110:111]
	s_waitcnt vmcnt(6)
	v_mov_b64_e32 v[102:103], v[122:123]
	v_mov_b64_e32 v[104:105], v[124:125]
	v_mov_b64_e32 v[106:107], v[206:207]
	v_mov_b64_e32 v[108:109], v[208:209]
	v_add_u32_e32 v96, 0x90, v188
	v_add_u32_e32 v92, 0xa0, v188
	v_add_u32_e32 v88, 0xb0, v188
	v_ashrrev_i32_e32 v97, 31, v96
	v_ashrrev_i32_e32 v93, 31, v92
	v_ashrrev_i32_e32 v89, 31, v88
	v_lshlrev_b64 v[98:99], 11, v[96:97]
	v_lshlrev_b64 v[94:95], 11, v[92:93]
	v_lshlrev_b64 v[90:91], 11, v[88:89]
	v_lshl_add_u64 v[64:65], v[186:187], 0, v[98:99]
	v_lshl_add_u64 v[66:67], v[186:187], 0, v[94:95]
	v_lshl_add_u64 v[114:115], v[186:187], 0, v[90:91]
	v_mov_b64_e32 v[84:85], v[210:211]
	v_mov_b64_e32 v[86:87], v[212:213]
	v_mov_b64_e32 v[80:81], v[214:215]
	v_mov_b64_e32 v[82:83], v[216:217]
	v_mov_b64_e32 v[76:77], v[218:219]
	v_mov_b64_e32 v[78:79], v[220:221]
	v_mov_b64_e32 v[72:73], v[222:223]
	v_mov_b64_e32 v[74:75], v[224:225]
	v_mov_b64_e32 v[68:69], v[226:227]
	v_mov_b64_e32 v[70:71], v[228:229]
	s_nop 0
	v_mov_b64_e32 v[64:65], v[248:249]
	v_mov_b64_e32 v[66:67], v[250:251]
	v_lshlrev_b32_e32 v114, 16, v102
	v_and_b32_e32 v115, 0xffff0000, v102
	v_lshlrev_b32_e32 v102, 16, v103
	v_and_b32_e32 v103, 0xffff0000, v103
	v_lshlrev_b32_e32 v116, 16, v104
	v_and_b32_e32 v117, 0xffff0000, v104
	v_lshlrev_b32_e32 v104, 16, v105
	v_and_b32_e32 v105, 0xffff0000, v105
	v_lshlrev_b32_e32 v118, 16, v106
	v_and_b32_e32 v119, 0xffff0000, v106
	v_lshlrev_b32_e32 v106, 16, v107
	v_and_b32_e32 v107, 0xffff0000, v107
	v_lshlrev_b32_e32 v120, 16, v108
	v_and_b32_e32 v121, 0xffff0000, v108
	v_lshlrev_b32_e32 v108, 16, v109
	v_and_b32_e32 v109, 0xffff0000, v109
	v_pk_fma_f32 v[62:63], v[62:63], 0.5, v[102:103] op_sel_hi:[1,0,1]
	v_pk_fma_f32 v[60:61], v[60:61], 0.5, v[114:115] op_sel_hi:[1,0,1]
	v_pk_fma_f32 v[58:59], v[58:59], 0.5, v[104:105] op_sel_hi:[1,0,1]
	v_pk_fma_f32 v[56:57], v[56:57], 0.5, v[116:117] op_sel_hi:[1,0,1]
	v_pk_fma_f32 v[54:55], v[54:55], 0.5, v[106:107] op_sel_hi:[1,0,1]
	v_pk_fma_f32 v[52:53], v[52:53], 0.5, v[118:119] op_sel_hi:[1,0,1]
	v_pk_fma_f32 v[102:103], v[50:51], 0.5, v[108:109] op_sel_hi:[1,0,1]
	v_pk_fma_f32 v[104:105], v[48:49], 0.5, v[120:121] op_sel_hi:[1,0,1]
	v_cvt_pk_bf16_f32 v48, v60, v61
	v_cvt_pk_bf16_f32 v49, v62, v63
	v_cvt_pk_bf16_f32 v50, v56, v57
	v_cvt_pk_bf16_f32 v51, v58, v59
	v_mul_f32_e32 v61, v61, v61
	v_mul_f32_e32 v63, v63, v63
	v_mul_f32_e32 v57, v57, v57
	v_mul_f32_e32 v59, v59, v59
	v_mul_f32_e32 v106, v53, v53
	v_mul_f32_e32 v107, v55, v55
	v_mul_f32_e32 v108, v105, v105
	v_mul_f32_e32 v109, v103, v103
	v_fmac_f32_e32 v61, v60, v60
	v_fmac_f32_e32 v63, v62, v62
	v_fmac_f32_e32 v57, v56, v56
	v_fmac_f32_e32 v59, v58, v58
	v_fmac_f32_e32 v106, v52, v52
	v_fmac_f32_e32 v107, v54, v54
	v_fmac_f32_e32 v108, v104, v104
	v_fmac_f32_e32 v109, v102, v102
	v_add_f32_e32 v56, v61, v63
	v_add_f32_e32 v57, v57, v59
	v_add_f32_e32 v58, v106, v107
	v_add_f32_e32 v59, v108, v109
	v_add_f32_e32 v56, v56, v57
	v_add_f32_e32 v57, v58, v59
	v_add_f32_e32 v58, v56, v57
	ds_bpermute_b32 v59, v204, v58
	v_lshl_add_u64 v[56:57], s[76:77], 0, v[110:111]
	v_lshl_add_u64 v[56:57], v[184:185], 1, v[56:57]
	global_store_dwordx4 v[56:57], v[48:51], off
	s_waitcnt lgkmcnt(0)
	s_nop 0
	v_add_f32_e32 v48, v58, v59
	ds_bpermute_b32 v49, v112, v48
	v_cvt_pk_bf16_f32 v50, v52, v53
	v_cvt_pk_bf16_f32 v51, v54, v55
	v_cvt_pk_bf16_f32 v52, v104, v105
	v_cvt_pk_bf16_f32 v53, v102, v103
	global_store_dwordx4 v[56:57], v[50:53], off offset:256
	s_and_saveexec_b64 s[24:25], s[8:9]
	s_cbranch_execz .LBB0_385
	v_lshlrev_b64 v[50:51], 6, v[100:101]
	v_lshl_add_u64 v[50:51], s[14:15], 0, v[50:51]
	v_lshl_add_u64 v[50:51], s[20:21], 2, v[50:51]
	s_lshl_b32 s4, s34, 2
	v_lshl_add_u64 v[50:51], v[50:51], 0, s[4:5]
	s_waitcnt lgkmcnt(0)
	v_add_f32_e32 v48, v48, v49
	global_store_dword v[50:51], v48, off
.LBB0_385:
	s_or_b64 exec, exec, s[24:25]
	v_lshlrev_b32_e32 v48, 16, v84
	s_waitcnt lgkmcnt(0)
	v_and_b32_e32 v49, 0xffff0000, v84
	v_lshlrev_b32_e32 v50, 16, v85
	v_and_b32_e32 v51, 0xffff0000, v85
	v_lshlrev_b32_e32 v52, 16, v86
	v_and_b32_e32 v53, 0xffff0000, v86
	v_pk_fma_f32 v[44:45], v[44:45], 0.5, v[48:49] op_sel_hi:[1,0,1]
	v_pk_fma_f32 v[46:47], v[46:47], 0.5, v[50:51] op_sel_hi:[1,0,1]
	v_pk_fma_f32 v[50:51], v[40:41], 0.5, v[52:53] op_sel_hi:[1,0,1]
	v_cvt_pk_bf16_f32 v40, v44, v45
	v_mul_f32_e32 v45, v45, v45
	v_lshlrev_b32_e32 v54, 16, v87
	v_and_b32_e32 v55, 0xffff0000, v87
	v_fmac_f32_e32 v45, v44, v44
	v_mul_f32_e32 v44, v47, v47
	v_pk_fma_f32 v[48:49], v[42:43], 0.5, v[54:55] op_sel_hi:[1,0,1]
	v_fmac_f32_e32 v44, v46, v46
	v_cvt_pk_bf16_f32 v41, v46, v47
	v_add_f32_e32 v44, v45, v44
	v_mul_f32_e32 v45, v51, v51
	v_mul_f32_e32 v46, v49, v49
	v_fmac_f32_e32 v45, v50, v50
	v_fmac_f32_e32 v46, v48, v48
	v_add_f32_e32 v45, v45, v46
	v_add_f32_e32 v52, v44, v45
	v_lshlrev_b32_e32 v44, 16, v80
	v_and_b32_e32 v45, 0xffff0000, v80
	v_lshlrev_b32_e32 v46, 16, v81
	v_and_b32_e32 v47, 0xffff0000, v81
	v_cvt_pk_bf16_f32 v42, v50, v51
	v_cvt_pk_bf16_f32 v43, v48, v49
	v_lshlrev_b32_e32 v48, 16, v82
	v_and_b32_e32 v49, 0xffff0000, v82
	v_pk_fma_f32 v[38:39], v[38:39], 0.5, v[46:47] op_sel_hi:[1,0,1]
	v_pk_fma_f32 v[36:37], v[36:37], 0.5, v[44:45] op_sel_hi:[1,0,1]
	v_lshlrev_b32_e32 v50, 16, v83
	v_and_b32_e32 v51, 0xffff0000, v83
	v_pk_fma_f32 v[46:47], v[32:33], 0.5, v[48:49] op_sel_hi:[1,0,1]
	v_mul_f32_e32 v32, v37, v37
	v_mul_f32_e32 v33, v39, v39
	v_pk_fma_f32 v[44:45], v[34:35], 0.5, v[50:51] op_sel_hi:[1,0,1]
	v_fmac_f32_e32 v32, v36, v36
	v_fmac_f32_e32 v33, v38, v38
	v_add_f32_e32 v32, v32, v33
	v_mul_f32_e32 v33, v47, v47
	v_mul_f32_e32 v34, v45, v45
	v_fmac_f32_e32 v33, v46, v46
	v_fmac_f32_e32 v34, v44, v44
	v_add_f32_e32 v33, v33, v34
	v_add_f32_e32 v32, v32, v33
	v_add_f32_e32 v35, v52, v32
	ds_bpermute_b32 v50, v204, v35
	v_lshl_add_u64 v[32:33], s[76:77], 0, v[98:99]
	v_lshl_add_u64 v[48:49], v[184:185], 1, v[32:33]
	global_store_dwordx4 v[48:49], v[40:43], off
	v_cvt_pk_bf16_f32 v34, v36, v37
	s_waitcnt lgkmcnt(0)
	v_add_f32_e32 v32, v35, v50
	ds_bpermute_b32 v33, v112, v32
	v_cvt_pk_bf16_f32 v35, v38, v39
	v_cvt_pk_bf16_f32 v36, v46, v47
	v_cvt_pk_bf16_f32 v37, v44, v45
	global_store_dwordx4 v[48:49], v[34:37], off offset:256
	s_and_saveexec_b64 s[24:25], s[8:9]
	s_cbranch_execz .LBB0_387
	v_lshlrev_b64 v[34:35], 6, v[96:97]
	v_lshl_add_u64 v[34:35], s[14:15], 0, v[34:35]
	v_lshl_add_u64 v[34:35], s[20:21], 2, v[34:35]
	s_lshl_b32 s4, s34, 2
	v_lshl_add_u64 v[34:35], v[34:35], 0, s[4:5]
	s_waitcnt lgkmcnt(0)
	v_add_f32_e32 v32, v32, v33
	global_store_dword v[34:35], v32, off
; __device__ __forceinline__ unsigned cvt_pk_bf16(float lo, float hi) { unsigned r; asm volatile("v_cvt_pk_bf16_f32 %0, %1, %2" : "=v"(r) : "v"(lo), "v"(hi)); return r; }
;     __device__ __forceinline__ void operator()(const f32x4 (&acc)[2][2][4][2], const Unit& u, int wr, int wc, int fr, int fq) const {
;     ...
;             for (int m = 0; m < 4; ++m) {
;                 const int row = row0 + ai * HALF + m * 16; const size_t off = (size_t)row * DM + col0; float q = 0.f;
; #pragma unroll
;                 for (int bj = 0; bj < 2; ++bj) {
;                     const size_t o2 = off + bj * HALF; f32x4 b0, b1;
;                     if (XI_BF16) bf8_to_f32(xin[0][m][bj], b0, b1); else { b0 = *(const f32x4*)(xi + o2); b1 = *(const f32x4*)(xi + o2 + 4); }
;                     const f32x4 o0 = b0 + acc[ai][bj][m][0] * scale, o1 = b1 + acc[ai][bj][m][1] * scale;
;                     u32x4 w; w.x = cvt_pk_bf16(o0[0], o0[1]); w.y = cvt_pk_bf16(o0[2], o0[3]); w.z = cvt_pk_bf16(o1[0], o1[1]); w.w = cvt_pk_bf16(o1[2], o1[3]);
;                     *(u32x4*)(xb + o2) = w;
;                     q += ((o0[0] * o0[0] + o0[1] * o0[1]) + (o0[2] * o0[2] + o0[3] * o0[3])) + ((o1[0] * o1[0] + o1[1] * o1[1]) + (o1[2] * o1[2] + o1[3] * o1[3]));
;                 }
;                 q += __shfl_xor(q, 16); q += __shfl_xor(q, 32);
;                 if (fq == 0) ssout[(size_t)row * 16 + u.pn * 4 + wc] = q;
.LBB0_387:
	s_or_b64 exec, exec, s[24:25]
	v_lshlrev_b32_e32 v32, 16, v76
	s_waitcnt lgkmcnt(0)
	v_and_b32_e32 v33, 0xffff0000, v76
	v_lshlrev_b32_e32 v34, 16, v77
	v_and_b32_e32 v35, 0xffff0000, v77
	v_lshlrev_b32_e32 v36, 16, v78
	v_and_b32_e32 v37, 0xffff0000, v78
	v_pk_fma_f32 v[28:29], v[28:29], 0.5, v[32:33] op_sel_hi:[1,0,1]
	v_pk_fma_f32 v[30:31], v[30:31], 0.5, v[34:35] op_sel_hi:[1,0,1]
	v_pk_fma_f32 v[34:35], v[24:25], 0.5, v[36:37] op_sel_hi:[1,0,1]
	v_cvt_pk_bf16_f32 v24, v28, v29
	v_mul_f32_e32 v29, v29, v29
	v_lshlrev_b32_e32 v38, 16, v79
	v_and_b32_e32 v39, 0xffff0000, v79
	v_fmac_f32_e32 v29, v28, v28
	v_mul_f32_e32 v28, v31, v31
	v_pk_fma_f32 v[32:33], v[26:27], 0.5, v[38:39] op_sel_hi:[1,0,1]
	v_fmac_f32_e32 v28, v30, v30
	v_cvt_pk_bf16_f32 v25, v30, v31
	v_add_f32_e32 v28, v29, v28
	v_mul_f32_e32 v29, v35, v35
	v_mul_f32_e32 v30, v33, v33
	v_fmac_f32_e32 v29, v34, v34
	v_fmac_f32_e32 v30, v32, v32
	v_add_f32_e32 v29, v29, v30
	v_add_f32_e32 v36, v28, v29
	v_lshlrev_b32_e32 v28, 16, v72
	v_and_b32_e32 v29, 0xffff0000, v72
	v_lshlrev_b32_e32 v30, 16, v73
	v_and_b32_e32 v31, 0xffff0000, v73
	v_cvt_pk_bf16_f32 v26, v34, v35
	v_cvt_pk_bf16_f32 v27, v32, v33
	v_lshlrev_b32_e32 v32, 16, v74
	v_and_b32_e32 v33, 0xffff0000, v74
	v_pk_fma_f32 v[22:23], v[22:23], 0.5, v[30:31] op_sel_hi:[1,0,1]
	v_pk_fma_f32 v[20:21], v[20:21], 0.5, v[28:29] op_sel_hi:[1,0,1]
	v_lshlrev_b32_e32 v34, 16, v75
	v_and_b32_e32 v35, 0xffff0000, v75
	v_pk_fma_f32 v[30:31], v[16:17], 0.5, v[32:33] op_sel_hi:[1,0,1]
	v_mul_f32_e32 v16, v21, v21
	v_mul_f32_e32 v17, v23, v23
	v_pk_fma_f32 v[28:29], v[18:19], 0.5, v[34:35] op_sel_hi:[1,0,1]
	v_fmac_f32_e32 v16, v20, v20
	v_fmac_f32_e32 v17, v22, v22
	v_add_f32_e32 v16, v16, v17
	v_mul_f32_e32 v17, v31, v31
	v_mul_f32_e32 v18, v29, v29
	v_fmac_f32_e32 v17, v30, v30
	v_fmac_f32_e32 v18, v28, v28
	v_add_f32_e32 v17, v17, v18
	v_add_f32_e32 v16, v16, v17
	v_add_f32_e32 v19, v36, v16
	ds_bpermute_b32 v34, v204, v19
	v_lshl_add_u64 v[16:17], s[76:77], 0, v[94:95]
	v_lshl_add_u64 v[32:33], v[184:185], 1, v[16:17]
	global_store_dwordx4 v[32:33], v[24:27], off
	v_cvt_pk_bf16_f32 v18, v20, v21
	s_waitcnt lgkmcnt(0)
	v_add_f32_e32 v16, v19, v34
	ds_bpermute_b32 v17, v112, v16
	v_cvt_pk_bf16_f32 v19, v22, v23
	v_cvt_pk_bf16_f32 v20, v30, v31
	v_cvt_pk_bf16_f32 v21, v28, v29
	global_store_dwordx4 v[32:33], v[18:21], off offset:256
	s_and_saveexec_b64 s[24:25], s[8:9]
	s_cbranch_execz .LBB0_389
	v_lshlrev_b64 v[18:19], 6, v[92:93]
	v_lshl_add_u64 v[18:19], s[14:15], 0, v[18:19]
	v_lshl_add_u64 v[18:19], s[20:21], 2, v[18:19]
	s_lshl_b32 s4, s34, 2
	v_lshl_add_u64 v[18:19], v[18:19], 0, s[4:5]
	s_waitcnt lgkmcnt(0)
	v_add_f32_e32 v16, v16, v17
	global_store_dword v[18:19], v16, off
.LBB0_389:
	s_or_b64 exec, exec, s[24:25]
	v_lshlrev_b32_e32 v16, 16, v68
	s_waitcnt lgkmcnt(0)
	v_and_b32_e32 v17, 0xffff0000, v68
	v_lshlrev_b32_e32 v18, 16, v69
	v_and_b32_e32 v19, 0xffff0000, v69
	v_lshlrev_b32_e32 v20, 16, v70
	v_and_b32_e32 v21, 0xffff0000, v70
	v_pk_fma_f32 v[12:13], v[12:13], 0.5, v[16:17] op_sel_hi:[1,0,1]
	v_pk_fma_f32 v[14:15], v[14:15], 0.5, v[18:19] op_sel_hi:[1,0,1]
	v_pk_fma_f32 v[18:19], v[8:9], 0.5, v[20:21] op_sel_hi:[1,0,1]
	v_cvt_pk_bf16_f32 v8, v12, v13
	v_mul_f32_e32 v13, v13, v13
	v_lshlrev_b32_e32 v22, 16, v71
	v_and_b32_e32 v23, 0xffff0000, v71
	v_fmac_f32_e32 v13, v12, v12
	v_mul_f32_e32 v12, v15, v15
	v_pk_fma_f32 v[16:17], v[10:11], 0.5, v[22:23] op_sel_hi:[1,0,1]
	v_fmac_f32_e32 v12, v14, v14
	v_cvt_pk_bf16_f32 v9, v14, v15
	v_add_f32_e32 v12, v13, v12
	v_mul_f32_e32 v13, v19, v19
	v_mul_f32_e32 v14, v17, v17
	v_fmac_f32_e32 v13, v18, v18
	v_fmac_f32_e32 v14, v16, v16
	v_add_f32_e32 v13, v13, v14
	v_add_f32_e32 v20, v12, v13
	v_lshlrev_b32_e32 v12, 16, v64
	v_and_b32_e32 v13, 0xffff0000, v64
	v_lshlrev_b32_e32 v14, 16, v65
	v_and_b32_e32 v15, 0xffff0000, v65
	v_cvt_pk_bf16_f32 v10, v18, v19
	v_cvt_pk_bf16_f32 v11, v16, v17
	v_lshlrev_b32_e32 v16, 16, v66
	v_and_b32_e32 v17, 0xffff0000, v66
	v_pk_fma_f32 v[6:7], v[6:7], 0.5, v[14:15] op_sel_hi:[1,0,1]
	v_pk_fma_f32 v[4:5], v[4:5], 0.5, v[12:13] op_sel_hi:[1,0,1]
	v_lshlrev_b32_e32 v18, 16, v67
	v_and_b32_e32 v19, 0xffff0000, v67
	v_pk_fma_f32 v[14:15], v[0:1], 0.5, v[16:17] op_sel_hi:[1,0,1]
	v_mul_f32_e32 v0, v5, v5
	v_mul_f32_e32 v1, v7, v7
	v_pk_fma_f32 v[12:13], v[2:3], 0.5, v[18:19] op_sel_hi:[1,0,1]
	v_fmac_f32_e32 v0, v4, v4
	v_fmac_f32_e32 v1, v6, v6
	v_add_f32_e32 v0, v0, v1
	v_mul_f32_e32 v1, v15, v15
	v_mul_f32_e32 v2, v13, v13
	v_fmac_f32_e32 v1, v14, v14
	v_fmac_f32_e32 v2, v12, v12
	v_add_f32_e32 v1, v1, v2
	v_add_f32_e32 v0, v0, v1
	v_add_f32_e32 v3, v20, v0
	ds_bpermute_b32 v18, v204, v3
	v_lshl_add_u64 v[0:1], s[76:77], 0, v[90:91]
	v_lshl_add_u64 v[16:17], v[184:185], 1, v[0:1]
	global_store_dwordx4 v[16:17], v[8:11], off
	v_cvt_pk_bf16_f32 v2, v4, v5
	s_waitcnt lgkmcnt(0)
	v_add_f32_e32 v0, v3, v18
	ds_bpermute_b32 v1, v112, v0
	v_cvt_pk_bf16_f32 v3, v6, v7
	v_cvt_pk_bf16_f32 v4, v14, v15
	v_cvt_pk_bf16_f32 v5, v12, v13
	global_store_dwordx4 v[16:17], v[2:5], off offset:256
	s_and_saveexec_b64 s[24:25], s[8:9]
	s_cbranch_execz .LBB0_391
	v_lshlrev_b64 v[2:3], 6, v[88:89]
	v_lshl_add_u64 v[2:3], s[14:15], 0, v[2:3]
	v_lshl_add_u64 v[2:3], s[20:21], 2, v[2:3]
	s_lshl_b32 s4, s34, 2
	v_lshl_add_u64 v[2:3], v[2:3], 0, s[4:5]
	s_waitcnt lgkmcnt(0)
	v_add_f32_e32 v0, v0, v1
	global_store_dword v[2:3], v0, off

; __device__ __forceinline__ unsigned cvt_pk_bf16(float lo, float hi) { unsigned r; asm volatile("v_cvt_pk_bf16_f32 %0, %1, %2" : "=v"(r) : "v"(lo), "v"(hi)); return r; }
;     __device__ __forceinline__ void operator()(const f32x4 (&acc)[2][2][4][2], const Unit& u, int wr, int wc, int fr, int fq) const {
;         const int row0 = u.pm * BM + wr * 64 + fr, col0 = u.pn * BM + wc * 32 + 8 * fq;
; #pragma unroll
;         for (int ai = 0; ai < 2; ++ai) {
;         u32x4 xin[1][4][2];
;         if (XI_BF16) {
; #pragma unroll
;                 for (int m = 0; m < 4; ++m)
; #pragma unroll
;                     for (int bj = 0; bj < 2; ++bj) xin[0][m][bj] = *(const u32x4*)(xb + (size_t)(row0 + ai * HALF + m * 16) * DM + col0 + bj * HALF);
;         }
; #pragma unroll
;             for (int m = 0; m < 4; ++m) {
;                 const int row = row0 + ai * HALF + m * 16; const size_t off = (size_t)row * DM + col0; float q = 0.f;
; #pragma unroll
;                 for (int bj = 0; bj < 2; ++bj) {
;                     const size_t o2 = off + bj * HALF; f32x4 b0, b1;
;                     if (XI_BF16) bf8_to_f32(xin[0][m][bj], b0, b1); else { b0 = *(const f32x4*)(xi + o2); b1 = *(const f32x4*)(xi + o2 + 4); }
;                     const f32x4 o0 = b0 + acc[ai][bj][m][0] * scale, o1 = b1 + acc[ai][bj][m][1] * scale;
;                     u32x4 w; w.x = cvt_pk_bf16(o0[0], o0[1]); w.y = cvt_pk_bf16(o0[2], o0[3]); w.z = cvt_pk_bf16(o1[0], o1[1]); w.w = cvt_pk_bf16(o1[2], o1[3]);
;                     *(u32x4*)(xb + o2) = w;
;                     q += ((o0[0] * o0[0] + o0[1] * o0[1]) + (o0[2] * o0[2] + o0[3] * o0[3])) + ((o1[0] * o1[0] + o1[1] * o1[1]) + (o1[2] * o1[2] + o1[3] * o1[3]));
;                 }
;                 q += __shfl_xor(q, 16); q += __shfl_xor(q, 32);
;                 if (fq == 0) ssout[(size_t)row * 16 + u.pn * 4 + wc] = q;
.LBB0_1235:
	s_or_b64 exec, exec, s[26:27]
	v_add_u32_e32 v126, 0x80, v186
	v_ashrrev_i32_e32 v127, 31, v126
	v_lshlrev_b64 v[126:127], 11, v[126:127]
	v_lshl_add_u64 v[126:127], v[184:185], 0, v[126:127]
	global_load_dwordx4 v[122:125], v[126:127], off
	global_load_dwordx4 v[206:209], v[126:127], off offset:256
	v_add_u32_e32 v238, 0x90, v186
	v_ashrrev_i32_e32 v239, 31, v238
	v_lshlrev_b64 v[238:239], 11, v[238:239]
	v_lshl_add_u64 v[238:239], v[184:185], 0, v[238:239]
	global_load_dwordx4 v[210:213], v[238:239], off
	global_load_dwordx4 v[214:217], v[238:239], off offset:256
	v_add_u32_e32 v126, 0xa0, v186
	v_ashrrev_i32_e32 v127, 31, v126
	v_lshlrev_b64 v[126:127], 11, v[126:127]
	v_lshl_add_u64 v[126:127], v[184:185], 0, v[126:127]
	global_load_dwordx4 v[218:221], v[126:127], off
	global_load_dwordx4 v[222:225], v[126:127], off offset:256
	v_add_u32_e32 v238, 0xb0, v186
	v_ashrrev_i32_e32 v239, 31, v238
	v_lshlrev_b64 v[238:239], 11, v[238:239]
	v_lshl_add_u64 v[238:239], v[184:185], 0, v[238:239]
	global_load_dwordx4 v[226:229], v[238:239], off
	global_load_dwordx4 v[246:249], v[238:239], off offset:256
	s_waitcnt lgkmcnt(0)
	v_lshlrev_b32_e32 v114, 16, v148
	v_and_b32_e32 v115, 0xffff0000, v148
	v_lshlrev_b32_e32 v116, 16, v149
	v_and_b32_e32 v117, 0xffff0000, v149
	v_lshlrev_b32_e32 v118, 16, v150
	v_and_b32_e32 v119, 0xffff0000, v150
	v_pk_add_f32 v[108:109], v[108:109], v[114:115]
	v_pk_add_f32 v[110:111], v[110:111], v[116:117]
	v_pk_add_f32 v[116:117], v[104:105], v[118:119]
	v_cvt_pk_bf16_f32 v104, v108, v109
	v_mul_f32_e32 v109, v109, v109
	v_lshlrev_b32_e32 v120, 16, v151
	v_and_b32_e32 v121, 0xffff0000, v151
	v_fmac_f32_e32 v109, v108, v108
	v_mul_f32_e32 v108, v111, v111
	v_pk_add_f32 v[114:115], v[106:107], v[120:121]
	v_fmac_f32_e32 v108, v110, v110
	v_cvt_pk_bf16_f32 v105, v110, v111
	v_add_f32_e32 v108, v109, v108
	v_mul_f32_e32 v109, v117, v117
	v_mul_f32_e32 v110, v115, v115
	v_fmac_f32_e32 v109, v116, v116
	v_fmac_f32_e32 v110, v114, v114
	v_add_f32_e32 v109, v109, v110
	v_add_f32_e32 v113, v108, v109
	v_lshlrev_b32_e32 v108, 16, v144
	v_and_b32_e32 v109, 0xffff0000, v144
	v_lshlrev_b32_e32 v110, 16, v145
	v_and_b32_e32 v111, 0xffff0000, v145
	v_cvt_pk_bf16_f32 v106, v116, v117
	v_cvt_pk_bf16_f32 v107, v114, v115
	v_lshlrev_b32_e32 v114, 16, v146
	v_and_b32_e32 v115, 0xffff0000, v146
	v_pk_add_f32 v[102:103], v[102:103], v[110:111]
	v_pk_add_f32 v[100:101], v[100:101], v[108:109]
	v_lshlrev_b32_e32 v116, 16, v147
	v_and_b32_e32 v117, 0xffff0000, v147
	v_pk_add_f32 v[110:111], v[96:97], v[114:115]
	v_mul_f32_e32 v96, v101, v101
	v_mul_f32_e32 v97, v103, v103
	v_pk_add_f32 v[108:109], v[98:99], v[116:117]
	v_fmac_f32_e32 v96, v100, v100
	v_fmac_f32_e32 v97, v102, v102
	v_add_f32_e32 v96, v96, v97
	v_mul_f32_e32 v97, v111, v111
	v_mul_f32_e32 v98, v109, v109
	v_fmac_f32_e32 v97, v110, v110
	v_fmac_f32_e32 v98, v108, v108
	v_add_f32_e32 v97, v97, v98
	v_add_f32_e32 v96, v96, v97
	v_add_f32_e32 v99, v113, v96
	ds_bpermute_b32 v113, v204, v99
	v_lshl_add_u64 v[96:97], s[76:77], 0, v[198:199]
	v_lshl_add_u64 v[114:115], v[182:183], 1, v[96:97]
	global_store_dwordx4 v[114:115], v[104:107], off
	v_cvt_pk_bf16_f32 v98, v100, v101
	s_waitcnt lgkmcnt(0)
	v_add_f32_e32 v96, v99, v113
	ds_bpermute_b32 v97, v112, v96
	v_cvt_pk_bf16_f32 v99, v102, v103
	v_cvt_pk_bf16_f32 v100, v110, v111
	v_cvt_pk_bf16_f32 v101, v108, v109
	global_store_dwordx4 v[114:115], v[98:101], off offset:256
	s_and_saveexec_b64 s[26:27], s[8:9]
	s_cbranch_execz .LBB0_1237
	v_lshlrev_b64 v[98:99], 6, v[196:197]
	v_lshl_add_u64 v[98:99], s[12:13], 0, v[98:99]
	v_lshl_add_u64 v[98:99], s[24:25], 2, v[98:99]
	s_lshl_b32 s0, s38, 2
	v_lshl_add_u64 v[98:99], v[98:99], 0, s[0:1]
	s_waitcnt lgkmcnt(0)
	v_add_f32_e32 v96, v96, v97
	global_store_dword v[98:99], v96, off

; __device__ __forceinline__ unsigned cvt_pk_bf16(float lo, float hi) { unsigned r; asm volatile("v_cvt_pk_bf16_f32 %0, %1, %2" : "=v"(r) : "v"(lo), "v"(hi)); return r; }
;     __device__ __forceinline__ void operator()(const f32x4 (&acc)[2][2][4][2], const Unit& u, int wr, int wc, int fr, int fq) const {
;     ...
;         for (int ai = 0; ai < 2; ++ai) {
;         u32x4 xin[1][4][2];
;         if (XI_BF16) {
; #pragma unroll
;                 for (int m = 0; m < 4; ++m)
; #pragma unroll
;                     for (int bj = 0; bj < 2; ++bj) xin[0][m][bj] = *(const u32x4*)(xb + (size_t)(row0 + ai * HALF + m * 16) * DM + col0 + bj * HALF);
;         }
; #pragma unroll
;             for (int m = 0; m < 4; ++m) {
;                 const int row = row0 + ai * HALF + m * 16; const size_t off = (size_t)row * DM + col0; float q = 0.f;
; #pragma unroll
;                 for (int bj = 0; bj < 2; ++bj) {
;                     const size_t o2 = off + bj * HALF; f32x4 b0, b1;
;                     if (XI_BF16) bf8_to_f32(xin[0][m][bj], b0, b1); else { b0 = *(const f32x4*)(xi + o2); b1 = *(const f32x4*)(xi + o2 + 4); }
;                     const f32x4 o0 = b0 + acc[ai][bj][m][0] * scale, o1 = b1 + acc[ai][bj][m][1] * scale;
;                     u32x4 w; w.x = cvt_pk_bf16(o0[0], o0[1]); w.y = cvt_pk_bf16(o0[2], o0[3]); w.z = cvt_pk_bf16(o1[0], o1[1]); w.w = cvt_pk_bf16(o1[2], o1[3]);
;                     *(u32x4*)(xb + o2) = w;
;                     q += ((o0[0] * o0[0] + o0[1] * o0[1]) + (o0[2] * o0[2] + o0[3] * o0[3])) + ((o1[0] * o1[0] + o1[1] * o1[1]) + (o1[2] * o1[2] + o1[3] * o1[3]));
;                 }
;                 q += __shfl_xor(q, 16); q += __shfl_xor(q, 32);
;                 if (fq == 0) ssout[(size_t)row * 16 + u.pn * 4 + wc] = q;
.LBB0_1241:
	s_or_b64 exec, exec, s[26:27]
	v_add_u32_e32 v100, 0x80, v186
	v_ashrrev_i32_e32 v101, 31, v100
	v_lshlrev_b64 v[110:111], 11, v[100:101]
	s_waitcnt lgkmcnt(0)
	v_lshl_add_u64 v[64:65], v[184:185], 0, v[110:111]
	s_waitcnt vmcnt(6)
	v_mov_b64_e32 v[102:103], v[122:123]
	v_mov_b64_e32 v[104:105], v[124:125]
	v_mov_b64_e32 v[106:107], v[206:207]
	v_mov_b64_e32 v[108:109], v[208:209]
	v_add_u32_e32 v96, 0x90, v186
	v_add_u32_e32 v92, 0xa0, v186
	v_add_u32_e32 v88, 0xb0, v186
	v_ashrrev_i32_e32 v97, 31, v96
	v_ashrrev_i32_e32 v93, 31, v92
	v_ashrrev_i32_e32 v89, 31, v88
	v_lshlrev_b64 v[98:99], 11, v[96:97]
	v_lshlrev_b64 v[94:95], 11, v[92:93]
	v_lshlrev_b64 v[90:91], 11, v[88:89]
	v_lshl_add_u64 v[64:65], v[184:185], 0, v[98:99]
	v_lshl_add_u64 v[66:67], v[184:185], 0, v[94:95]
	v_lshl_add_u64 v[114:115], v[184:185], 0, v[90:91]
	v_mov_b64_e32 v[84:85], v[210:211]
	v_mov_b64_e32 v[86:87], v[212:213]
	v_mov_b64_e32 v[80:81], v[214:215]
	v_mov_b64_e32 v[82:83], v[216:217]
	v_mov_b64_e32 v[76:77], v[218:219]
	v_mov_b64_e32 v[78:79], v[220:221]
	v_mov_b64_e32 v[72:73], v[222:223]
	v_mov_b64_e32 v[74:75], v[224:225]
	v_mov_b64_e32 v[68:69], v[226:227]
	v_mov_b64_e32 v[70:71], v[228:229]
	s_nop 0
	v_mov_b64_e32 v[64:65], v[246:247]
	v_mov_b64_e32 v[66:67], v[248:249]
	v_lshlrev_b32_e32 v114, 16, v102
	v_and_b32_e32 v115, 0xffff0000, v102
	v_lshlrev_b32_e32 v102, 16, v103
	v_and_b32_e32 v103, 0xffff0000, v103
	v_lshlrev_b32_e32 v116, 16, v104
	v_and_b32_e32 v117, 0xffff0000, v104
	v_lshlrev_b32_e32 v104, 16, v105
	v_and_b32_e32 v105, 0xffff0000, v105
	v_lshlrev_b32_e32 v118, 16, v106
	v_and_b32_e32 v119, 0xffff0000, v106
	v_lshlrev_b32_e32 v106, 16, v107
	v_and_b32_e32 v107, 0xffff0000, v107
	v_lshlrev_b32_e32 v120, 16, v108
	v_and_b32_e32 v121, 0xffff0000, v108
	v_lshlrev_b32_e32 v108, 16, v109
	v_and_b32_e32 v109, 0xffff0000, v109
	v_pk_add_f32 v[62:63], v[62:63], v[102:103]
	v_pk_add_f32 v[60:61], v[60:61], v[114:115]
	v_pk_add_f32 v[58:59], v[58:59], v[104:105]
	v_pk_add_f32 v[56:57], v[56:57], v[116:117]
	v_pk_add_f32 v[54:55], v[54:55], v[106:107]
	v_pk_add_f32 v[52:53], v[52:53], v[118:119]
	v_pk_add_f32 v[102:103], v[50:51], v[108:109]
	v_pk_add_f32 v[104:105], v[48:49], v[120:121]
	v_cvt_pk_bf16_f32 v48, v60, v61
	v_cvt_pk_bf16_f32 v49, v62, v63
	v_cvt_pk_bf16_f32 v50, v56, v57
	v_cvt_pk_bf16_f32 v51, v58, v59
	v_mul_f32_e32 v61, v61, v61
	v_mul_f32_e32 v63, v63, v63
	v_mul_f32_e32 v57, v57, v57
	v_mul_f32_e32 v59, v59, v59
	v_mul_f32_e32 v106, v53, v53
	v_mul_f32_e32 v107, v55, v55
	v_mul_f32_e32 v108, v105, v105
	v_mul_f32_e32 v109, v103, v103
	v_fmac_f32_e32 v61, v60, v60
	v_fmac_f32_e32 v63, v62, v62
	v_fmac_f32_e32 v57, v56, v56
	v_fmac_f32_e32 v59, v58, v58
	v_fmac_f32_e32 v106, v52, v52
	v_fmac_f32_e32 v107, v54, v54
	v_fmac_f32_e32 v108, v104, v104
	v_fmac_f32_e32 v109, v102, v102
	v_add_f32_e32 v56, v61, v63
	v_add_f32_e32 v57, v57, v59
	v_add_f32_e32 v58, v106, v107
	v_add_f32_e32 v59, v108, v109
	v_add_f32_e32 v56, v56, v57
	v_add_f32_e32 v57, v58, v59
	v_add_f32_e32 v58, v56, v57
	ds_bpermute_b32 v59, v204, v58
	v_lshl_add_u64 v[56:57], s[76:77], 0, v[110:111]
	v_lshl_add_u64 v[56:57], v[182:183], 1, v[56:57]
	global_store_dwordx4 v[56:57], v[48:51], off
	s_waitcnt lgkmcnt(0)
	s_nop 0
	v_add_f32_e32 v48, v58, v59
	ds_bpermute_b32 v49, v112, v48
	v_cvt_pk_bf16_f32 v50, v52, v53
	v_cvt_pk_bf16_f32 v51, v54, v55
	v_cvt_pk_bf16_f32 v52, v104, v105
	v_cvt_pk_bf16_f32 v53, v102, v103
	global_store_dwordx4 v[56:57], v[50:53], off offset:256
	s_and_saveexec_b64 s[26:27], s[8:9]
	s_cbranch_execz .LBB0_1243
	v_lshlrev_b64 v[50:51], 6, v[100:101]
	v_lshl_add_u64 v[50:51], s[12:13], 0, v[50:51]
	v_lshl_add_u64 v[50:51], s[24:25], 2, v[50:51]
	s_lshl_b32 s0, s38, 2
	v_lshl_add_u64 v[50:51], v[50:51], 0, s[0:1]
	s_waitcnt lgkmcnt(0)
	v_add_f32_e32 v48, v48, v49
	global_store_dword v[50:51], v48, off
.LBB0_1243:
	s_or_b64 exec, exec, s[26:27]
	v_lshlrev_b32_e32 v48, 16, v84
	s_waitcnt lgkmcnt(0)
	v_and_b32_e32 v49, 0xffff0000, v84
	v_lshlrev_b32_e32 v50, 16, v85
	v_and_b32_e32 v51, 0xffff0000, v85
	v_lshlrev_b32_e32 v52, 16, v86
	v_and_b32_e32 v53, 0xffff0000, v86
	v_pk_add_f32 v[44:45], v[44:45], v[48:49]
	v_pk_add_f32 v[46:47], v[46:47], v[50:51]
	v_pk_add_f32 v[50:51], v[40:41], v[52:53]
	v_cvt_pk_bf16_f32 v40, v44, v45
	v_mul_f32_e32 v45, v45, v45
	v_lshlrev_b32_e32 v54, 16, v87
	v_and_b32_e32 v55, 0xffff0000, v87
	v_fmac_f32_e32 v45, v44, v44
	v_mul_f32_e32 v44, v47, v47
	v_pk_add_f32 v[48:49], v[42:43], v[54:55]
	v_fmac_f32_e32 v44, v46, v46
	v_cvt_pk_bf16_f32 v41, v46, v47
	v_add_f32_e32 v44, v45, v44
	v_mul_f32_e32 v45, v51, v51
	v_mul_f32_e32 v46, v49, v49
	v_fmac_f32_e32 v45, v50, v50
	v_fmac_f32_e32 v46, v48, v48
	v_add_f32_e32 v45, v45, v46
	v_add_f32_e32 v52, v44, v45
	v_lshlrev_b32_e32 v44, 16, v80
	v_and_b32_e32 v45, 0xffff0000, v80
	v_lshlrev_b32_e32 v46, 16, v81
	v_and_b32_e32 v47, 0xffff0000, v81
	v_cvt_pk_bf16_f32 v42, v50, v51
	v_cvt_pk_bf16_f32 v43, v48, v49
	v_lshlrev_b32_e32 v48, 16, v82
	v_and_b32_e32 v49, 0xffff0000, v82
	v_pk_add_f32 v[38:39], v[38:39], v[46:47]
	v_pk_add_f32 v[36:37], v[36:37], v[44:45]
	v_lshlrev_b32_e32 v50, 16, v83
	v_and_b32_e32 v51, 0xffff0000, v83
	v_pk_add_f32 v[46:47], v[32:33], v[48:49]
	v_mul_f32_e32 v32, v37, v37
	v_mul_f32_e32 v33, v39, v39
	v_pk_add_f32 v[44:45], v[34:35], v[50:51]
	v_fmac_f32_e32 v32, v36, v36
	v_fmac_f32_e32 v33, v38, v38
	v_add_f32_e32 v32, v32, v33
	v_mul_f32_e32 v33, v47, v47
	v_mul_f32_e32 v34, v45, v45
	v_fmac_f32_e32 v33, v46, v46
	v_fmac_f32_e32 v34, v44, v44
	v_add_f32_e32 v33, v33, v34
	v_add_f32_e32 v32, v32, v33
	v_add_f32_e32 v35, v52, v32
	ds_bpermute_b32 v50, v204, v35
	v_lshl_add_u64 v[32:33], s[76:77], 0, v[98:99]
	v_lshl_add_u64 v[48:49], v[182:183], 1, v[32:33]
	global_store_dwordx4 v[48:49], v[40:43], off
	v_cvt_pk_bf16_f32 v34, v36, v37
	s_waitcnt lgkmcnt(0)
	v_add_f32_e32 v32, v35, v50
	ds_bpermute_b32 v33, v112, v32
	v_cvt_pk_bf16_f32 v35, v38, v39
	v_cvt_pk_bf16_f32 v36, v46, v47
	v_cvt_pk_bf16_f32 v37, v44, v45
	global_store_dwordx4 v[48:49], v[34:37], off offset:256
	s_and_saveexec_b64 s[26:27], s[8:9]
	s_cbranch_execz .LBB0_1245
	v_lshlrev_b64 v[34:35], 6, v[96:97]
	v_lshl_add_u64 v[34:35], s[12:13], 0, v[34:35]
	v_lshl_add_u64 v[34:35], s[24:25], 2, v[34:35]
	s_lshl_b32 s0, s38, 2
	v_lshl_add_u64 v[34:35], v[34:35], 0, s[0:1]
	s_waitcnt lgkmcnt(0)
	v_add_f32_e32 v32, v32, v33
	global_store_dword v[34:35], v32, off
; __device__ __forceinline__ unsigned cvt_pk_bf16(float lo, float hi) { unsigned r; asm volatile("v_cvt_pk_bf16_f32 %0, %1, %2" : "=v"(r) : "v"(lo), "v"(hi)); return r; }
;     __device__ __forceinline__ void operator()(const f32x4 (&acc)[2][2][4][2], const Unit& u, int wr, int wc, int fr, int fq) const {
;     ...
;             for (int m = 0; m < 4; ++m) {
;                 const int row = row0 + ai * HALF + m * 16; const size_t off = (size_t)row * DM + col0; float q = 0.f;
; #pragma unroll
;                 for (int bj = 0; bj < 2; ++bj) {
;                     const size_t o2 = off + bj * HALF; f32x4 b0, b1;
;                     if (XI_BF16) bf8_to_f32(xin[0][m][bj], b0, b1); else { b0 = *(const f32x4*)(xi + o2); b1 = *(const f32x4*)(xi + o2 + 4); }
;                     const f32x4 o0 = b0 + acc[ai][bj][m][0] * scale, o1 = b1 + acc[ai][bj][m][1] * scale;
;                     u32x4 w; w.x = cvt_pk_bf16(o0[0], o0[1]); w.y = cvt_pk_bf16(o0[2], o0[3]); w.z = cvt_pk_bf16(o1[0], o1[1]); w.w = cvt_pk_bf16(o1[2], o1[3]);
;                     *(u32x4*)(xb + o2) = w;
;                     q += ((o0[0] * o0[0] + o0[1] * o0[1]) + (o0[2] * o0[2] + o0[3] * o0[3])) + ((o1[0] * o1[0] + o1[1] * o1[1]) + (o1[2] * o1[2] + o1[3] * o1[3]));
;                 }
;                 q += __shfl_xor(q, 16); q += __shfl_xor(q, 32);
;                 if (fq == 0) ssout[(size_t)row * 16 + u.pn * 4 + wc] = q;
.LBB0_1245:
	s_or_b64 exec, exec, s[26:27]
	v_lshlrev_b32_e32 v32, 16, v76
	s_waitcnt lgkmcnt(0)
	v_and_b32_e32 v33, 0xffff0000, v76
	v_lshlrev_b32_e32 v34, 16, v77
	v_and_b32_e32 v35, 0xffff0000, v77
	v_lshlrev_b32_e32 v36, 16, v78
	v_and_b32_e32 v37, 0xffff0000, v78
	v_pk_add_f32 v[28:29], v[28:29], v[32:33]
	v_pk_add_f32 v[30:31], v[30:31], v[34:35]
	v_pk_add_f32 v[34:35], v[24:25], v[36:37]
	v_cvt_pk_bf16_f32 v24, v28, v29
	v_mul_f32_e32 v29, v29, v29
	v_lshlrev_b32_e32 v38, 16, v79
	v_and_b32_e32 v39, 0xffff0000, v79
	v_fmac_f32_e32 v29, v28, v28
	v_mul_f32_e32 v28, v31, v31
	v_pk_add_f32 v[32:33], v[26:27], v[38:39]
	v_fmac_f32_e32 v28, v30, v30
	v_cvt_pk_bf16_f32 v25, v30, v31
	v_add_f32_e32 v28, v29, v28
	v_mul_f32_e32 v29, v35, v35
	v_mul_f32_e32 v30, v33, v33
	v_fmac_f32_e32 v29, v34, v34
	v_fmac_f32_e32 v30, v32, v32
	v_add_f32_e32 v29, v29, v30
	v_add_f32_e32 v36, v28, v29
	v_lshlrev_b32_e32 v28, 16, v72
	v_and_b32_e32 v29, 0xffff0000, v72
	v_lshlrev_b32_e32 v30, 16, v73
	v_and_b32_e32 v31, 0xffff0000, v73
	v_cvt_pk_bf16_f32 v26, v34, v35
	v_cvt_pk_bf16_f32 v27, v32, v33
	v_lshlrev_b32_e32 v32, 16, v74
	v_and_b32_e32 v33, 0xffff0000, v74
	v_pk_add_f32 v[22:23], v[22:23], v[30:31]
	v_pk_add_f32 v[20:21], v[20:21], v[28:29]
	v_lshlrev_b32_e32 v34, 16, v75
	v_and_b32_e32 v35, 0xffff0000, v75
	v_pk_add_f32 v[30:31], v[16:17], v[32:33]
	v_mul_f32_e32 v16, v21, v21
	v_mul_f32_e32 v17, v23, v23
	v_pk_add_f32 v[28:29], v[18:19], v[34:35]
	v_fmac_f32_e32 v16, v20, v20
	v_fmac_f32_e32 v17, v22, v22
	v_add_f32_e32 v16, v16, v17
	v_mul_f32_e32 v17, v31, v31
	v_mul_f32_e32 v18, v29, v29
	v_fmac_f32_e32 v17, v30, v30
	v_fmac_f32_e32 v18, v28, v28
	v_add_f32_e32 v17, v17, v18
	v_add_f32_e32 v16, v16, v17
	v_add_f32_e32 v19, v36, v16
	ds_bpermute_b32 v34, v204, v19
	v_lshl_add_u64 v[16:17], s[76:77], 0, v[94:95]
	v_lshl_add_u64 v[32:33], v[182:183], 1, v[16:17]
	global_store_dwordx4 v[32:33], v[24:27], off
	v_cvt_pk_bf16_f32 v18, v20, v21
	s_waitcnt lgkmcnt(0)
	v_add_f32_e32 v16, v19, v34
	ds_bpermute_b32 v17, v112, v16
	v_cvt_pk_bf16_f32 v19, v22, v23
	v_cvt_pk_bf16_f32 v20, v30, v31
	v_cvt_pk_bf16_f32 v21, v28, v29
	global_store_dwordx4 v[32:33], v[18:21], off offset:256
	s_and_saveexec_b64 s[26:27], s[8:9]
	s_cbranch_execz .LBB0_1247
	v_lshlrev_b64 v[18:19], 6, v[92:93]
	v_lshl_add_u64 v[18:19], s[12:13], 0, v[18:19]
	v_lshl_add_u64 v[18:19], s[24:25], 2, v[18:19]
	s_lshl_b32 s0, s38, 2
	v_lshl_add_u64 v[18:19], v[18:19], 0, s[0:1]
	s_waitcnt lgkmcnt(0)
	v_add_f32_e32 v16, v16, v17
	global_store_dword v[18:19], v16, off
.LBB0_1247:
	s_or_b64 exec, exec, s[26:27]
	v_lshlrev_b32_e32 v16, 16, v68
	s_waitcnt lgkmcnt(0)
	v_and_b32_e32 v17, 0xffff0000, v68
	v_lshlrev_b32_e32 v18, 16, v69
	v_and_b32_e32 v19, 0xffff0000, v69
	v_lshlrev_b32_e32 v20, 16, v70
	v_and_b32_e32 v21, 0xffff0000, v70
	v_pk_add_f32 v[12:13], v[12:13], v[16:17]
	v_pk_add_f32 v[14:15], v[14:15], v[18:19]
	v_pk_add_f32 v[18:19], v[8:9], v[20:21]
	v_cvt_pk_bf16_f32 v8, v12, v13
	v_mul_f32_e32 v13, v13, v13
	v_lshlrev_b32_e32 v22, 16, v71
	v_and_b32_e32 v23, 0xffff0000, v71
	v_fmac_f32_e32 v13, v12, v12
	v_mul_f32_e32 v12, v15, v15
	v_pk_add_f32 v[16:17], v[10:11], v[22:23]
	v_fmac_f32_e32 v12, v14, v14
	v_cvt_pk_bf16_f32 v9, v14, v15
	v_add_f32_e32 v12, v13, v12
	v_mul_f32_e32 v13, v19, v19
	v_mul_f32_e32 v14, v17, v17
	v_fmac_f32_e32 v13, v18, v18
	v_fmac_f32_e32 v14, v16, v16
	v_add_f32_e32 v13, v13, v14
	v_add_f32_e32 v20, v12, v13
	v_lshlrev_b32_e32 v12, 16, v64
	v_and_b32_e32 v13, 0xffff0000, v64
	v_lshlrev_b32_e32 v14, 16, v65
	v_and_b32_e32 v15, 0xffff0000, v65
	v_cvt_pk_bf16_f32 v10, v18, v19
	v_cvt_pk_bf16_f32 v11, v16, v17
	v_lshlrev_b32_e32 v16, 16, v66
	v_and_b32_e32 v17, 0xffff0000, v66
	v_pk_add_f32 v[6:7], v[6:7], v[14:15]
	v_pk_add_f32 v[4:5], v[4:5], v[12:13]
	v_lshlrev_b32_e32 v18, 16, v67
	v_and_b32_e32 v19, 0xffff0000, v67
	v_pk_add_f32 v[14:15], v[0:1], v[16:17]
	v_mul_f32_e32 v0, v5, v5
	v_mul_f32_e32 v1, v7, v7
	v_pk_add_f32 v[12:13], v[2:3], v[18:19]
	v_fmac_f32_e32 v0, v4, v4
	v_fmac_f32_e32 v1, v6, v6
	v_add_f32_e32 v0, v0, v1
	v_mul_f32_e32 v1, v15, v15
	v_mul_f32_e32 v2, v13, v13
	v_fmac_f32_e32 v1, v14, v14
	v_fmac_f32_e32 v2, v12, v12
	v_add_f32_e32 v1, v1, v2
	v_add_f32_e32 v0, v0, v1
	v_add_f32_e32 v3, v20, v0
	ds_bpermute_b32 v18, v204, v3
	v_lshl_add_u64 v[0:1], s[76:77], 0, v[90:91]
	v_lshl_add_u64 v[16:17], v[182:183], 1, v[0:1]
	global_store_dwordx4 v[16:17], v[8:11], off
	v_cvt_pk_bf16_f32 v2, v4, v5
	s_waitcnt lgkmcnt(0)
	v_add_f32_e32 v0, v3, v18
	ds_bpermute_b32 v1, v112, v0
	v_cvt_pk_bf16_f32 v3, v6, v7
	v_cvt_pk_bf16_f32 v4, v14, v15
	v_cvt_pk_bf16_f32 v5, v12, v13
	global_store_dwordx4 v[16:17], v[2:5], off offset:256
	s_and_saveexec_b64 s[26:27], s[8:9]
	s_cbranch_execz .LBB0_1249
	v_lshlrev_b64 v[2:3], 6, v[88:89]
	v_lshl_add_u64 v[2:3], s[12:13], 0, v[2:3]
	v_lshl_add_u64 v[2:3], s[24:25], 2, v[2:3]
	s_lshl_b32 s0, s38, 2
	v_lshl_add_u64 v[2:3], v[2:3], 0, s[0:1]
	s_waitcnt lgkmcnt(0)
	v_add_f32_e32 v0, v0, v1
	global_store_dword v[2:3], v0, off
